# on top of the loop-edge edits: half 2's seven leading p1 exps issued between the K reads and their wait
# speedup vs baseline: 1.0015x; 1.0015x over previous
; __device__ __forceinline__ void finishSM(f32x16& p0, f32x16& p1, float alpha, float& l_reg, bf16x8& pa0, bf16x8& pa1, bf16x8& pa2, bf16x8& pa3) {
;   for (int r = 0; r < 16; ++r) p1[r] = __builtin_amdgcn_exp2f(p1[r]);
;   float ps = 0; for (int r = 0; r < 16; ++r) ps += p0[r]; for (int r = 0; r < 16; ++r) ps += p1[r];
;   asm volatile("" : "+v"(ps));
;   l_reg = l_reg * alpha + ps;
;     ...
;   PK4(p0, 0, pa0); PK4(p0, 8, pa1); PK4(p1, 0, pa2); PK4(p1, 8, pa3);
;     ...
; }
; __device__ __forceinline__ void qkt(f32x16& p0, f32x16& p1, const bf16* Ks, const bf16x8* qr, int r32, int hi) {
;   p0 = f32x16{}; p1 = f32x16{};
;   for (int d0 = 0; d0 < 8; ++d0) { int cb = (d0 * 16 + hi * 8) * 2;
;     bf16x8 b0 = *reinterpret_cast<const bf16x8*>((const char*)Ks + KSWZ(r32, cb));
;     bf16x8 b1 = *reinterpret_cast<const bf16x8*>((const char*)Ks + KSWZ(32 + r32, cb));
;     p0 = __builtin_amdgcn_mfma_f32_32x32x16_bf16(b0, qr[d0], p0, 0, 0, 0);
;     p1 = __builtin_amdgcn_mfma_f32_32x32x16_bf16(b1, qr[d0], p1, 0, 0, 0); }
; }
; __device__ __forceinline__ int v_st(int k, int c) { const int kk = k;
;   return ((kk >> 3) * 4 + (c >> 5)) * 512 + ((kk & 7) * 32 + (c & 31)) * 2; }
; __device__ __forceinline__ int v_rd_base(int lane) { return ((lane & 3) << 3) | (((lane >> 2) & 3) << 6) | (((lane >> 4) & 1) << 5) | (((lane >> 5) & 1) << 8); }
; template <int OFF> __device__ __forceinline__ s16x4 tr_read(int vb) {
;   s16x4 r; asm volatile("ds_read_b64_tr_b16 %0, %1 offset:%2" : "=&v"(r) : "v"(vb), "i"(OFF) : "memory"); return r;
; }
; template <int D0> __device__ __forceinline__ void pv_one(f32x16& od, int vb, bf16x8 pa0, bf16x8 pa1, bf16x8 pa2, bf16x8 pa3) {
;   const s16x4 l0 = tr_read<v_rd_off(D0, 0, 0)>(vb), h0 = tr_read<v_rd_off(D0, 0, 1)>(vb), l1 = tr_read<v_rd_off(D0, 1, 0)>(vb), h1 = tr_read<v_rd_off(D0, 1, 1)>(vb);
;   const s16x4 l2 = tr_read<v_rd_off(D0, 2, 0)>(vb), h2 = tr_read<v_rd_off(D0, 2, 1)>(vb), l3 = tr_read<v_rd_off(D0, 3, 0)>(vb), h3 = tr_read<v_rd_off(D0, 3, 1)>(vb);
;   asm volatile("s_waitcnt lgkmcnt(0)" ::: "memory"); SBAR();
;     ...
;   od = __builtin_amdgcn_mfma_f32_32x32x16_bf16(pa0, PK(l0, h0), od, 0, 0, 0);
;   od = __builtin_amdgcn_mfma_f32_32x32x16_bf16(pa1, PK(l1, h1), od, 0, 0, 0);
;   od = __builtin_amdgcn_mfma_f32_32x32x16_bf16(pa2, PK(l2, h2), od, 0, 0, 0);
;   od = __builtin_amdgcn_mfma_f32_32x32x16_bf16(pa3, PK(l3, h3), od, 0, 0, 0);
;     ...
; }
.Lat461_a_go:
	s_waitcnt lgkmcnt(3)
	v_mfma_f32_32x32x16_bf16 v[96:111], v[80:83], v[136:139], 0
	v_exp_f32_e32 v238, v64
	v_add_f32_e32 v64, v197, v196
	v_add_f32_e32 v64, v193, v64
	v_add_f32_e32 v64, v195, v64
	s_waitcnt lgkmcnt(2)
	v_mfma_f32_32x32x16_bf16 v[80:95], v[84:87], v[136:139], 0
	v_add_f32_e32 v64, v191, v64
	v_add_f32_e32 v64, v194, v64
	v_add_f32_e32 v64, v190, v64
	v_add_f32_e32 v64, v192, v64
	v_add_f32_e32 v64, v169, v64
	v_add_f32_e32 v64, v171, v64
	s_waitcnt lgkmcnt(1)
	v_mfma_f32_32x32x16_bf16 v[96:111], v[198:201], v[140:143], v[96:111]
	v_add_f32_e32 v64, v167, v64
	v_add_f32_e32 v64, v170, v64
	v_add_f32_e32 v64, v165, v64
	v_add_f32_e32 v64, v168, v64
	v_add_f32_e32 v64, v164, v64
	v_add_f32_e32 v64, v166, v64
	v_exp_f32_e32 v239, v68
	s_waitcnt lgkmcnt(0)
	v_mfma_f32_32x32x16_bf16 v[80:95], v[202:205], v[140:143], v[80:95]
	ds_read_b128 v[198:201], v180 offset:16384
	ds_read_b128 v[202:205], v180 offset:24576
	v_add_f32_e32 v64, v238, v64
	v_exp_f32_e32 v240, v69
	v_exp_f32_e32 v241, v70
	v_exp_f32_e32 v242, v71
	s_waitcnt lgkmcnt(1)
	v_mfma_f32_32x32x16_bf16 v[96:111], v[198:201], v[132:135], v[96:111]
	ds_read_b128 v[198:201], v181 offset:16384
	ds_read_b128 v[206:209], v181 offset:24576
	ds_read_b128 v[210:213], v182 offset:16384
	ds_read_b128 v[214:217], v182 offset:24576
	ds_read_b128 v[218:221], v183 offset:16384
	ds_read_b128 v[222:225], v183 offset:24576
	v_exp_f32_e32 v243, v76
	v_exp_f32_e32 v244, v77
	v_exp_f32_e32 v245, v78
	v_exp_f32_e32 v79, v79
	s_waitcnt lgkmcnt(6)
	v_mfma_f32_32x32x16_bf16 v[80:95], v[202:205], v[132:135], v[80:95]
	ds_read_b128 v[202:205], v184 offset:16384
	ds_read_b128 v[226:229], v184 offset:24576
	ds_read_b128 v[230:233], v185 offset:16384
	ds_read_b128 v[234:237], v185 offset:24576
	s_waitcnt lgkmcnt(9)
	v_mfma_f32_32x32x16_bf16 v[96:111], v[198:201], v[128:131], v[96:111]
	v_exp_f32_e32 v199, v65
	v_exp_f32_e32 v200, v66
	v_exp_f32_e32 v201, v67
	v_add_f32_e32 v64, v199, v64
	v_add_f32_e32 v64, v200, v64
	v_add_f32_e32 v64, v201, v64
	s_waitcnt lgkmcnt(8)
	v_mfma_f32_32x32x16_bf16 v[80:95], v[206:209], v[128:131], v[80:95]
	v_exp_f32_e32 v206, v72
	v_add_f32_e32 v64, v239, v64
	v_exp_f32_e32 v207, v73
	v_add_f32_e32 v64, v240, v64
	v_exp_f32_e32 v208, v74
	v_add_f32_e32 v64, v241, v64
	v_exp_f32_e32 v209, v75
	s_waitcnt lgkmcnt(7)
	v_mfma_f32_32x32x16_bf16 v[96:111], v[210:213], v[124:127], v[96:111]
	v_add_f32_e32 v64, v242, v64
	v_add_f32_e32 v64, v206, v64
	v_add_f32_e32 v64, v207, v64
	v_add_f32_e32 v64, v208, v64
	v_add_f32_e32 v64, v209, v64
	v_add_f32_e32 v64, v243, v64
	v_add_f32_e32 v64, v244, v64
	s_waitcnt lgkmcnt(6)
	v_mfma_f32_32x32x16_bf16 v[80:95], v[214:217], v[124:127], v[80:95]
	v_add_f32_e32 v64, v245, v64
	v_add_f32_e32 v198, v79, v64
	v_cvt_pk_bf16_f32 v64, v196, v197
	v_cvt_pk_bf16_f32 v65, v193, v195
	v_cvt_pk_bf16_f32 v66, v191, v194
	v_cvt_pk_bf16_f32 v67, v190, v192
	s_waitcnt lgkmcnt(5)
	v_mfma_f32_32x32x16_bf16 v[96:111], v[218:221], v[120:123], v[96:111]
	v_cvt_pk_bf16_f32 v68, v169, v171
	v_cvt_pk_bf16_f32 v69, v167, v170
	v_cvt_pk_bf16_f32 v70, v165, v168
	v_cvt_pk_bf16_f32 v71, v164, v166
	v_cvt_pk_bf16_f32 v72, v238, v199
	v_cvt_pk_bf16_f32 v73, v200, v201
	v_cvt_pk_bf16_f32 v74, v239, v240
	s_waitcnt lgkmcnt(4)
	v_mfma_f32_32x32x16_bf16 v[80:95], v[222:225], v[120:123], v[80:95]
	v_cvt_pk_bf16_f32 v75, v241, v242
	v_cvt_pk_bf16_f32 v76, v206, v207
	v_cvt_pk_bf16_f32 v77, v208, v209
	v_cvt_pk_bf16_f32 v78, v243, v244
	v_cvt_pk_bf16_f32 v79, v245, v79
	s_waitcnt lgkmcnt(3)
	v_mfma_f32_32x32x16_bf16 v[96:111], v[202:205], v[116:119], v[96:111]
	s_add_i32 s33, s40, 0x8000
	s_and_b32 s43, s33, 0xc000
	ds_read_b64_tr_b16 v[190:191], v176
	ds_read_b64_tr_b16 v[192:193], v176 offset:2048
	ds_read_b64_tr_b16 v[194:195], v176 offset:4096
	ds_read_b64_tr_b16 v[196:197], v176 offset:6144
	s_waitcnt lgkmcnt(6)
	v_mfma_f32_32x32x16_bf16 v[80:95], v[226:229], v[116:119], v[80:95]
	ds_read_b64_tr_b16 v[200:201], v176 offset:8192
	ds_read_b64_tr_b16 v[202:203], v176 offset:10240
	ds_read_b64_tr_b16 v[204:205], v176 offset:12288
	ds_read_b64_tr_b16 v[206:207], v176 offset:14336
	s_add_i32 s74, s40, 0x4000
	s_and_b32 s74, s74, 0xc000
	s_add_u32 s98, s38, s22
	s_addc_u32 s99, s39, s23
	s_add_i32 s41, s67, s74
	s_add_u32 s100, s38, s24
	s_addc_u32 s101, s39, s25
	s_mov_b32 m0, s41
	s_add_i32 s74, s72, s74
	global_load_lds_dwordx4 v156, s[98:99]
	s_waitcnt lgkmcnt(9)
	v_mfma_f32_32x32x16_bf16 v[96:111], v[230:233], v[112:115], v[96:111]
	s_add_i32 m0, s41, 0x2000
	s_nop 0
	global_load_lds_dwordx4 v158, s[98:99]
	s_mov_b32 m0, s74
	s_nop 0
	global_load_lds_dwordx4 v162, s[100:101]
	s_waitcnt lgkmcnt(8)
	v_mfma_f32_32x32x16_bf16 v[80:95], v[234:237], v[112:115], v[80:95]
	s_add_i32 m0, s74, 0x2000
	s_nop 0
	global_load_lds_dwordx4 v160, s[100:101]
	s_nop 0
	s_waitcnt lgkmcnt(6)
	v_mfma_f32_32x32x16_bf16 v[48:63], v[64:67], v[190:193], v[48:63]
	v_exp_f32_e32 v232, v96
	ds_read_b64_tr_b16 v[190:191], v176 offset:512
	ds_read_b64_tr_b16 v[192:193], v176 offset:2560
	s_waitcnt lgkmcnt(6)
; #define SBAR() __builtin_amdgcn_sched_barrier(0)
; #define PUBLISH(n) do { asm volatile("s_waitcnt vmcnt(" #n ")" ::: "memory"); asm volatile("s_waitcnt lgkmcnt(0)" ::: "memory"); __builtin_amdgcn_s_barrier(); SBAR(); } while (0)
; template <int D0> __device__ __forceinline__ void pv_one(f32x16& od, int vb, bf16x8 pa0, bf16x8 pa1, bf16x8 pa2, bf16x8 pa3) {
;   const s16x4 l0 = tr_read<v_rd_off(D0, 0, 0)>(vb), h0 = tr_read<v_rd_off(D0, 0, 1)>(vb), l1 = tr_read<v_rd_off(D0, 1, 0)>(vb), h1 = tr_read<v_rd_off(D0, 1, 1)>(vb);
;   const s16x4 l2 = tr_read<v_rd_off(D0, 2, 0)>(vb), h2 = tr_read<v_rd_off(D0, 2, 1)>(vb), l3 = tr_read<v_rd_off(D0, 3, 0)>(vb), h3 = tr_read<v_rd_off(D0, 3, 1)>(vb);
;   asm volatile("s_waitcnt lgkmcnt(0)" ::: "memory"); SBAR();
;     ...
;   od = __builtin_amdgcn_mfma_f32_32x32x16_bf16(pa0, PK(l0, h0), od, 0, 0, 0);
;   od = __builtin_amdgcn_mfma_f32_32x32x16_bf16(pa1, PK(l1, h1), od, 0, 0, 0);
;   od = __builtin_amdgcn_mfma_f32_32x32x16_bf16(pa2, PK(l2, h2), od, 0, 0, 0);
;   od = __builtin_amdgcn_mfma_f32_32x32x16_bf16(pa3, PK(l3, h3), od, 0, 0, 0);
;     ...
; }
; __device__ __forceinline__ void pv_d0(f32x16* o, int vb, bf16x8 pa0, bf16x8 pa1, bf16x8 pa2, bf16x8 pa3) {
;   pv_one<0>(o[0], vb, pa0, pa1, pa2, pa3); pv_one<1>(o[1], vb, pa0, pa1, pa2, pa3); pv_one<2>(o[2], vb, pa0, pa1, pa2, pa3); pv_one<3>(o[3], vb, pa0, pa1, pa2, pa3);
; }
; template <typename TQ> ...
;     ...
;   for (int j = 1; j + 1 < NT; j += 2) {
;     SBAR(); qkt(pB0, pB1, (const bf16*)(K_lds + (j & 3) * (int)SHM_K), qr, r32, hi);
;     finishSM(pA0, pA1, alA, l_reg, pa0, pa1, pa2, pa3); SBAR();
;     DMA_TILE(j + 2, (j + 2) & 3); SBAR();
;     pv_d0(o, vb0 + ((j - 1) & 3) * (int)SHM_V, pa0, pa1, pa2, pa3); partialSM<true>(pB0, pB1, m_reg, mnB, alB);
;     PUBLISH(4);
;     SBAR(); qkt(pA0, pA1, (const bf16*)(K_lds + ((j + 1) & 3) * (int)SHM_K), qr, r32, hi);
;     finishSM(pB0, pB1, alB, l_reg, pa0, pa1, pa2, pa3); SBAR();
;     if (j + 3 < NT) { DMA_TILE(j + 3, (j + 3) & 3); } SBAR();
	v_mfma_f32_32x32x16_bf16 v[48:63], v[68:71], v[194:197], v[48:63]
	v_exp_f32_e32 v233, v97
	ds_read_b64_tr_b16 v[194:195], v176 offset:4608
	ds_read_b64_tr_b16 v[196:197], v176 offset:6656
	s_waitcnt lgkmcnt(6)
	v_mfma_f32_32x32x16_bf16 v[48:63], v[72:75], v[200:203], v[48:63]
	v_exp_f32_e32 v234, v98
	ds_read_b64_tr_b16 v[200:201], v176 offset:8704
	ds_read_b64_tr_b16 v[202:203], v176 offset:10752
	ds_read_b64_tr_b16 v[208:209], v176 offset:12800
	ds_read_b64_tr_b16 v[210:211], v176 offset:14848
	s_waitcnt lgkmcnt(8)
	v_mfma_f32_32x32x16_bf16 v[48:63], v[76:79], v[204:207], v[48:63]
	v_exp_f32_e32 v235, v99
	s_waitcnt lgkmcnt(6)
	v_mfma_f32_32x32x16_bf16 v[32:47], v[64:67], v[190:193], v[32:47]
	v_exp_f32_e32 v236, v100
	ds_read_b64_tr_b16 v[190:191], v176 offset:1024
	ds_read_b64_tr_b16 v[192:193], v176 offset:3072
	s_waitcnt lgkmcnt(6)
	v_mfma_f32_32x32x16_bf16 v[32:47], v[68:71], v[194:197], v[32:47]
	v_exp_f32_e32 v237, v101
	ds_read_b64_tr_b16 v[194:195], v176 offset:5120
	ds_read_b64_tr_b16 v[196:197], v176 offset:7168
	s_waitcnt lgkmcnt(6)
	v_mfma_f32_32x32x16_bf16 v[32:47], v[72:75], v[200:203], v[32:47]
	v_exp_f32_e32 v238, v102
	ds_read_b64_tr_b16 v[200:201], v176 offset:9216
	ds_read_b64_tr_b16 v[202:203], v176 offset:11264
	ds_read_b64_tr_b16 v[204:205], v176 offset:13312
	ds_read_b64_tr_b16 v[206:207], v176 offset:15360
	s_waitcnt lgkmcnt(8)
	v_mfma_f32_32x32x16_bf16 v[32:47], v[76:79], v[208:211], v[32:47]
	v_exp_f32_e32 v239, v103
	v_exp_f32_e32 v240, v104
	s_waitcnt lgkmcnt(6)
	v_mfma_f32_32x32x16_bf16 v[16:31], v[64:67], v[190:193], v[16:31]
	v_exp_f32_e32 v241, v105
	ds_read_b64_tr_b16 v[190:191], v176 offset:1536
	ds_read_b64_tr_b16 v[192:193], v176 offset:3584
	s_waitcnt lgkmcnt(6)
	v_mfma_f32_32x32x16_bf16 v[16:31], v[68:71], v[194:197], v[16:31]
	v_exp_f32_e32 v242, v106
	ds_read_b64_tr_b16 v[194:195], v176 offset:5632
	ds_read_b64_tr_b16 v[196:197], v176 offset:7680
	s_waitcnt lgkmcnt(6)
	v_mfma_f32_32x32x16_bf16 v[16:31], v[72:75], v[200:203], v[16:31]
	v_exp_f32_e32 v243, v107
	ds_read_b64_tr_b16 v[200:201], v176 offset:9728
	ds_read_b64_tr_b16 v[202:203], v176 offset:11776
	ds_read_b64_tr_b16 v[208:209], v176 offset:13824
	ds_read_b64_tr_b16 v[210:211], v176 offset:15872
	s_waitcnt lgkmcnt(8)
	v_mfma_f32_32x32x16_bf16 v[16:31], v[76:79], v[204:207], v[16:31]
	v_exp_f32_e32 v244, v108
	s_waitcnt lgkmcnt(6)
	v_mfma_f32_32x32x16_bf16 v[0:15], v[64:67], v[190:193], v[0:15]
	v_exp_f32_e32 v245, v109
	s_waitcnt lgkmcnt(4)
	v_mfma_f32_32x32x16_bf16 v[0:15], v[68:71], v[194:197], v[0:15]
	v_exp_f32_e32 v246, v110
	s_waitcnt lgkmcnt(2)
	v_mfma_f32_32x32x16_bf16 v[0:15], v[72:75], v[200:203], v[0:15]
	v_exp_f32_e32 v247, v111
	s_waitcnt vmcnt(4)
	s_waitcnt lgkmcnt(0)
	s_barrier
	s_and_b32 s40, s40, 0xc000
	s_add_i32 s40, s57, s40
	ds_read_b128 v[64:67], v178 offset:32768
	ds_read_b128 v[68:71], v178 offset:40960
	ds_read_b128 v[190:193], v179 offset:32768
	ds_read_b128 v[194:197], v179 offset:40960
	v_mfma_f32_32x32x16_bf16 v[0:15], v[76:79], v[208:211], v[0:15]
	v_exp_f32_e32 v80, v80
	v_exp_f32_e32 v81, v81
	v_exp_f32_e32 v82, v82
	v_exp_f32_e32 v83, v83
	v_exp_f32_e32 v87, v87
	v_exp_f32_e32 v248, v93
	v_exp_f32_e32 v249, v94
	s_waitcnt lgkmcnt(3)
	v_mfma_f32_32x32x16_bf16 v[96:111], v[64:67], v[136:139], 0
	s_waitcnt lgkmcnt(2)
	v_mfma_f32_32x32x16_bf16 v[64:79], v[68:71], v[136:139], 0
	s_waitcnt lgkmcnt(1)
	v_mfma_f32_32x32x16_bf16 v[96:111], v[190:193], v[140:143], v[96:111]
	s_waitcnt lgkmcnt(0)
	v_mfma_f32_32x32x16_bf16 v[64:79], v[194:197], v[140:143], v[64:79]
	ds_read_b128 v[190:193], v180 offset:32768
	ds_read_b128 v[194:197], v180 offset:40960
	s_waitcnt lgkmcnt(1)
	v_mfma_f32_32x32x16_bf16 v[96:111], v[190:193], v[132:135], v[96:111]
	ds_read_b128 v[190:193], v181 offset:32768
	ds_read_b128 v[200:203], v181 offset:40960
	ds_read_b128 v[204:207], v182 offset:32768
	ds_read_b128 v[208:211], v182 offset:40960
	ds_read_b128 v[212:215], v183 offset:32768
	ds_read_b128 v[216:219], v183 offset:40960
	s_waitcnt lgkmcnt(6)
	v_mfma_f32_32x32x16_bf16 v[64:79], v[194:197], v[132:135], v[64:79]
	ds_read_b128 v[194:197], v184 offset:32768
	ds_read_b128 v[220:223], v184 offset:40960
	ds_read_b128 v[224:227], v185 offset:32768
	ds_read_b128 v[228:231], v185 offset:40960
	s_waitcnt lgkmcnt(9)
	v_mfma_f32_32x32x16_bf16 v[96:111], v[190:193], v[128:131], v[96:111]
	s_cmp_ge_u32 s73, s37
	s_cselect_b64 s[40:41], -1, 0
	s_and_b64 vcc, exec, s[40:41]
	s_cbranch_vccnz .LBB0_463
	s_add_i32 s74, s67, s43
	s_add_u32 s98, s38, s26
	s_addc_u32 s99, s39, s27
	s_mov_b32 m0, s74
	s_add_i32 s43, s72, s43
	global_load_lds_dwordx4 v156, s[98:99]
	s_add_u32 s100, s38, s28
	s_addc_u32 s101, s39, s29
	s_add_i32 m0, s74, 0x2000
	s_nop 0
	global_load_lds_dwordx4 v158, s[98:99]
	s_mov_b32 m0, s43
	s_nop 0
	global_load_lds_dwordx4 v162, s[100:101]
	s_add_i32 m0, s43, 0x2000
	s_nop 0
	global_load_lds_dwordx4 v160, s[100:101]

; #define SBAR() __builtin_amdgcn_sched_barrier(0)
; #define PK4(P, BASE, OUT) do { u32x4 w = {cvtpk(P[BASE + 0], P[BASE + 1]), cvtpk(P[BASE + 2], P[BASE + 3]), cvtpk(P[BASE + 4], P[BASE + 5]), cvtpk(P[BASE + 6], P[BASE + 7])}; \
;     OUT = *reinterpret_cast<bf16x8*>(&w); } while (0)
; __device__ __forceinline__ void finishSM(f32x16& p0, f32x16& p1, float alpha, float& l_reg, bf16x8& pa0, bf16x8& pa1, bf16x8& pa2, bf16x8& pa3) {
;   for (int r = 0; r < 16; ++r) p1[r] = __builtin_amdgcn_exp2f(p1[r]);
;   float ps = 0; for (int r = 0; r < 16; ++r) ps += p0[r]; for (int r = 0; r < 16; ++r) ps += p1[r];
;   asm volatile("" : "+v"(ps));
;   l_reg = l_reg * alpha + ps;
;     ...
;   PK4(p0, 0, pa0); PK4(p0, 8, pa1); PK4(p1, 0, pa2); PK4(p1, 8, pa3);
;     ...
; }
; __device__ __forceinline__ void qkt(f32x16& p0, f32x16& p1, const bf16* Ks, const bf16x8* qr, int r32, int hi) {
;   p0 = f32x16{}; p1 = f32x16{};
;   for (int d0 = 0; d0 < 8; ++d0) { int cb = (d0 * 16 + hi * 8) * 2;
;     bf16x8 b0 = *reinterpret_cast<const bf16x8*>((const char*)Ks + KSWZ(r32, cb));
;     bf16x8 b1 = *reinterpret_cast<const bf16x8*>((const char*)Ks + KSWZ(32 + r32, cb));
;     p0 = __builtin_amdgcn_mfma_f32_32x32x16_bf16(b0, qr[d0], p0, 0, 0, 0);
;     p1 = __builtin_amdgcn_mfma_f32_32x32x16_bf16(b1, qr[d0], p1, 0, 0, 0); }
; }
; template <typename TQ> ...
;     ...
;   for (int j = 1; j + 1 < NT; j += 2) {
;     SBAR(); qkt(pB0, pB1, (const bf16*)(K_lds + (j & 3) * (int)SHM_K), qr, r32, hi);
;     finishSM(pA0, pA1, alA, l_reg, pa0, pa1, pa2, pa3); SBAR();
;     DMA_TILE(j + 2, (j + 2) & 3); SBAR();
;     pv_d0(o, vb0 + ((j - 1) & 3) * (int)SHM_V, pa0, pa1, pa2, pa3); partialSM<true>(pB0, pB1, m_reg, mnB, alB);
.Lat461_b:
.Lat461_b_in:
	s_mov_b32 s40, s33
	s_addk_i32 s33, 0xc000
	s_and_b32 s42, s33, 0xc000
	s_add_i32 s33, s57, s42
	ds_read_b128 v[80:83], v178 offset:49152
	ds_read_b128 v[84:87], v178 offset:57344
	ds_read_b128 v[198:201], v179 offset:49152
	ds_read_b128 v[202:205], v179 offset:57344
	v_exp_f32_e32 v196, v96
	v_exp_f32_e32 v197, v97
	v_exp_f32_e32 v193, v98
	v_exp_f32_e32 v195, v99
	v_exp_f32_e32 v191, v100
	v_exp_f32_e32 v194, v101
	v_exp_f32_e32 v190, v102
	v_exp_f32_e32 v192, v103
	v_exp_f32_e32 v169, v104
	v_exp_f32_e32 v171, v105
	v_exp_f32_e32 v167, v106
	v_exp_f32_e32 v170, v107
	v_exp_f32_e32 v165, v108
	v_exp_f32_e32 v168, v109
	v_exp_f32_e32 v164, v110
	v_exp_f32_e32 v166, v111
	s_waitcnt lgkmcnt(3)
	v_mfma_f32_32x32x16_bf16 v[96:111], v[80:83], v[136:139], 0
	v_exp_f32_e32 v238, v64
	v_add_f32_e32 v64, v197, v196
	v_add_f32_e32 v64, v193, v64
	v_add_f32_e32 v64, v195, v64
	s_waitcnt lgkmcnt(2)
	v_mfma_f32_32x32x16_bf16 v[80:95], v[84:87], v[136:139], 0
	v_add_f32_e32 v64, v191, v64
	v_add_f32_e32 v64, v194, v64
	v_add_f32_e32 v64, v190, v64
	v_add_f32_e32 v64, v192, v64
	v_add_f32_e32 v64, v169, v64
	v_add_f32_e32 v64, v171, v64
	s_waitcnt lgkmcnt(1)
	v_mfma_f32_32x32x16_bf16 v[96:111], v[198:201], v[140:143], v[96:111]
	v_add_f32_e32 v64, v167, v64
	v_add_f32_e32 v64, v170, v64
	v_add_f32_e32 v64, v165, v64
	v_add_f32_e32 v64, v168, v64
	v_add_f32_e32 v64, v164, v64
	v_add_f32_e32 v64, v166, v64
	v_exp_f32_e32 v239, v68
	s_waitcnt lgkmcnt(0)
	v_mfma_f32_32x32x16_bf16 v[80:95], v[202:205], v[140:143], v[80:95]
	ds_read_b128 v[198:201], v180 offset:49152
	ds_read_b128 v[202:205], v180 offset:57344
	v_add_f32_e32 v64, v238, v64
	v_exp_f32_e32 v240, v69
	v_exp_f32_e32 v241, v70
	v_exp_f32_e32 v242, v71
	s_waitcnt lgkmcnt(1)
	v_mfma_f32_32x32x16_bf16 v[96:111], v[198:201], v[132:135], v[96:111]
	ds_read_b128 v[198:201], v181 offset:49152
	ds_read_b128 v[206:209], v181 offset:57344
	ds_read_b128 v[210:213], v182 offset:49152
	ds_read_b128 v[214:217], v182 offset:57344
	ds_read_b128 v[218:221], v183 offset:49152
	ds_read_b128 v[222:225], v183 offset:57344
	v_exp_f32_e32 v243, v76
	v_exp_f32_e32 v244, v77
	v_exp_f32_e32 v245, v78
	v_exp_f32_e32 v79, v79
	s_waitcnt lgkmcnt(6)
	v_mfma_f32_32x32x16_bf16 v[80:95], v[202:205], v[132:135], v[80:95]
	ds_read_b128 v[202:205], v184 offset:49152
	ds_read_b128 v[226:229], v184 offset:57344
	ds_read_b128 v[230:233], v185 offset:49152
	ds_read_b128 v[234:237], v185 offset:57344
	s_waitcnt lgkmcnt(9)
	v_mfma_f32_32x32x16_bf16 v[96:111], v[198:201], v[128:131], v[96:111]
	v_exp_f32_e32 v199, v65
	v_exp_f32_e32 v200, v66
	v_exp_f32_e32 v201, v67
	v_add_f32_e32 v64, v199, v64
	v_add_f32_e32 v64, v200, v64
	v_add_f32_e32 v64, v201, v64
	s_waitcnt lgkmcnt(8)
	v_mfma_f32_32x32x16_bf16 v[80:95], v[206:209], v[128:131], v[80:95]
	v_exp_f32_e32 v206, v72
	v_add_f32_e32 v64, v239, v64
	v_exp_f32_e32 v207, v73
	v_add_f32_e32 v64, v240, v64
	v_exp_f32_e32 v208, v74
	v_add_f32_e32 v64, v241, v64
	v_exp_f32_e32 v209, v75
	s_waitcnt lgkmcnt(7)
	v_mfma_f32_32x32x16_bf16 v[96:111], v[210:213], v[124:127], v[96:111]
	v_add_f32_e32 v64, v242, v64
	v_add_f32_e32 v64, v206, v64
	v_add_f32_e32 v64, v207, v64
	v_add_f32_e32 v64, v208, v64
	v_add_f32_e32 v64, v209, v64
	v_add_f32_e32 v64, v243, v64
	v_add_f32_e32 v64, v244, v64
	s_waitcnt lgkmcnt(6)
	v_mfma_f32_32x32x16_bf16 v[80:95], v[214:217], v[124:127], v[80:95]
	v_add_f32_e32 v64, v245, v64
	v_add_f32_e32 v198, v79, v64
	v_cvt_pk_bf16_f32 v64, v196, v197
	v_cvt_pk_bf16_f32 v65, v193, v195
	v_cvt_pk_bf16_f32 v66, v191, v194
	v_cvt_pk_bf16_f32 v67, v190, v192
	s_waitcnt lgkmcnt(5)
	v_mfma_f32_32x32x16_bf16 v[96:111], v[218:221], v[120:123], v[96:111]
	v_cvt_pk_bf16_f32 v68, v169, v171
	v_cvt_pk_bf16_f32 v69, v167, v170
	v_cvt_pk_bf16_f32 v70, v165, v168
	v_cvt_pk_bf16_f32 v71, v164, v166
	v_cvt_pk_bf16_f32 v72, v238, v199
	v_cvt_pk_bf16_f32 v73, v200, v201
	v_cvt_pk_bf16_f32 v74, v239, v240
	s_waitcnt lgkmcnt(4)
	v_mfma_f32_32x32x16_bf16 v[80:95], v[222:225], v[120:123], v[80:95]
	v_cvt_pk_bf16_f32 v75, v241, v242
	v_cvt_pk_bf16_f32 v76, v206, v207
	v_cvt_pk_bf16_f32 v77, v208, v209
	v_cvt_pk_bf16_f32 v78, v243, v244
	v_cvt_pk_bf16_f32 v79, v245, v79
	s_waitcnt lgkmcnt(3)
	v_mfma_f32_32x32x16_bf16 v[96:111], v[202:205], v[116:119], v[96:111]
	s_add_i32 s33, s40, 0x8000
	s_and_b32 s43, s33, 0xc000
	ds_read_b64_tr_b16 v[190:191], v176 offset:32768
	ds_read_b64_tr_b16 v[192:193], v176 offset:34816
	ds_read_b64_tr_b16 v[194:195], v176 offset:36864
	ds_read_b64_tr_b16 v[196:197], v176 offset:38912
	s_waitcnt lgkmcnt(6)
	v_mfma_f32_32x32x16_bf16 v[80:95], v[226:229], v[116:119], v[80:95]
	ds_read_b64_tr_b16 v[200:201], v176 offset:40960
	ds_read_b64_tr_b16 v[202:203], v176 offset:43008
	ds_read_b64_tr_b16 v[204:205], v176 offset:45056
	ds_read_b64_tr_b16 v[206:207], v176 offset:47104
	s_add_i32 s74, s40, 0x4000
	s_and_b32 s74, s74, 0xc000
	s_add_u32 s98, s38, s22
	s_addc_u32 s99, s39, s23
	s_add_i32 s41, s67, s74
	s_add_u32 s100, s38, s24
	s_addc_u32 s101, s39, s25
	s_mov_b32 m0, s41
	s_add_i32 s74, s72, s74
	global_load_lds_dwordx4 v156, s[98:99]
	s_waitcnt lgkmcnt(9)
; #define SBAR() __builtin_amdgcn_sched_barrier(0)
; #define PUBLISH(n) do { asm volatile("s_waitcnt vmcnt(" #n ")" ::: "memory"); asm volatile("s_waitcnt lgkmcnt(0)" ::: "memory"); __builtin_amdgcn_s_barrier(); SBAR(); } while (0)
; template <int D0> __device__ __forceinline__ void pv_one(f32x16& od, int vb, bf16x8 pa0, bf16x8 pa1, bf16x8 pa2, bf16x8 pa3) {
;   const s16x4 l0 = tr_read<v_rd_off(D0, 0, 0)>(vb), h0 = tr_read<v_rd_off(D0, 0, 1)>(vb), l1 = tr_read<v_rd_off(D0, 1, 0)>(vb), h1 = tr_read<v_rd_off(D0, 1, 1)>(vb);
;   const s16x4 l2 = tr_read<v_rd_off(D0, 2, 0)>(vb), h2 = tr_read<v_rd_off(D0, 2, 1)>(vb), l3 = tr_read<v_rd_off(D0, 3, 0)>(vb), h3 = tr_read<v_rd_off(D0, 3, 1)>(vb);
;   asm volatile("s_waitcnt lgkmcnt(0)" ::: "memory"); SBAR();
;     ...
;   od = __builtin_amdgcn_mfma_f32_32x32x16_bf16(pa0, PK(l0, h0), od, 0, 0, 0);
;   od = __builtin_amdgcn_mfma_f32_32x32x16_bf16(pa1, PK(l1, h1), od, 0, 0, 0);
;   od = __builtin_amdgcn_mfma_f32_32x32x16_bf16(pa2, PK(l2, h2), od, 0, 0, 0);
;   od = __builtin_amdgcn_mfma_f32_32x32x16_bf16(pa3, PK(l3, h3), od, 0, 0, 0);
;     ...
; }
; __device__ __forceinline__ void pv_d0(f32x16* o, int vb, bf16x8 pa0, bf16x8 pa1, bf16x8 pa2, bf16x8 pa3) {
;   pv_one<0>(o[0], vb, pa0, pa1, pa2, pa3); pv_one<1>(o[1], vb, pa0, pa1, pa2, pa3); pv_one<2>(o[2], vb, pa0, pa1, pa2, pa3); pv_one<3>(o[3], vb, pa0, pa1, pa2, pa3);
; }
; template <typename TQ> ...
;     ...
;   for (int j = 1; j + 1 < NT; j += 2) {
;     SBAR(); qkt(pB0, pB1, (const bf16*)(K_lds + (j & 3) * (int)SHM_K), qr, r32, hi);
;     finishSM(pA0, pA1, alA, l_reg, pa0, pa1, pa2, pa3); SBAR();
;     DMA_TILE(j + 2, (j + 2) & 3); SBAR();
;     pv_d0(o, vb0 + ((j - 1) & 3) * (int)SHM_V, pa0, pa1, pa2, pa3); partialSM<true>(pB0, pB1, m_reg, mnB, alB);
;     PUBLISH(4);
;     SBAR(); qkt(pA0, pA1, (const bf16*)(K_lds + ((j + 1) & 3) * (int)SHM_K), qr, r32, hi);
;     finishSM(pB0, pB1, alB, l_reg, pa0, pa1, pa2, pa3); SBAR();
;     if (j + 3 < NT) { DMA_TILE(j + 3, (j + 3) & 3); } SBAR();
	v_mfma_f32_32x32x16_bf16 v[96:111], v[230:233], v[112:115], v[96:111]
	s_add_i32 m0, s41, 0x2000
	s_nop 0
	global_load_lds_dwordx4 v158, s[98:99]
	s_mov_b32 m0, s74
	s_nop 0
	global_load_lds_dwordx4 v162, s[100:101]
	s_waitcnt lgkmcnt(8)
	v_mfma_f32_32x32x16_bf16 v[80:95], v[234:237], v[112:115], v[80:95]
	s_add_i32 m0, s74, 0x2000
	s_nop 0
	global_load_lds_dwordx4 v160, s[100:101]
	s_nop 0
	s_waitcnt lgkmcnt(6)
	v_mfma_f32_32x32x16_bf16 v[48:63], v[64:67], v[190:193], v[48:63]
	v_exp_f32_e32 v232, v96
	ds_read_b64_tr_b16 v[190:191], v176 offset:33280
	ds_read_b64_tr_b16 v[192:193], v176 offset:35328
	s_waitcnt lgkmcnt(6)
	v_mfma_f32_32x32x16_bf16 v[48:63], v[68:71], v[194:197], v[48:63]
	v_exp_f32_e32 v233, v97
	ds_read_b64_tr_b16 v[194:195], v176 offset:37376
	ds_read_b64_tr_b16 v[196:197], v176 offset:39424
	s_waitcnt lgkmcnt(6)
	v_mfma_f32_32x32x16_bf16 v[48:63], v[72:75], v[200:203], v[48:63]
	v_exp_f32_e32 v234, v98
	ds_read_b64_tr_b16 v[200:201], v176 offset:41472
	ds_read_b64_tr_b16 v[202:203], v176 offset:43520
	ds_read_b64_tr_b16 v[208:209], v176 offset:45568
	ds_read_b64_tr_b16 v[210:211], v176 offset:47616
	s_waitcnt lgkmcnt(8)
	v_mfma_f32_32x32x16_bf16 v[48:63], v[76:79], v[204:207], v[48:63]
	v_exp_f32_e32 v235, v99
	s_waitcnt lgkmcnt(6)
	v_mfma_f32_32x32x16_bf16 v[32:47], v[64:67], v[190:193], v[32:47]
	v_exp_f32_e32 v236, v100
	ds_read_b64_tr_b16 v[190:191], v176 offset:33792
	ds_read_b64_tr_b16 v[192:193], v176 offset:35840
	s_waitcnt lgkmcnt(6)
	v_mfma_f32_32x32x16_bf16 v[32:47], v[68:71], v[194:197], v[32:47]
	v_exp_f32_e32 v237, v101
	ds_read_b64_tr_b16 v[194:195], v176 offset:37888
	ds_read_b64_tr_b16 v[196:197], v176 offset:39936
	s_waitcnt lgkmcnt(6)
	v_mfma_f32_32x32x16_bf16 v[32:47], v[72:75], v[200:203], v[32:47]
	v_exp_f32_e32 v238, v102
	ds_read_b64_tr_b16 v[200:201], v176 offset:41984
	ds_read_b64_tr_b16 v[202:203], v176 offset:44032
	ds_read_b64_tr_b16 v[204:205], v176 offset:46080
	ds_read_b64_tr_b16 v[206:207], v176 offset:48128
	s_waitcnt lgkmcnt(8)
	v_mfma_f32_32x32x16_bf16 v[32:47], v[76:79], v[208:211], v[32:47]
	v_exp_f32_e32 v239, v103
	v_exp_f32_e32 v240, v104
	s_waitcnt lgkmcnt(6)
	v_mfma_f32_32x32x16_bf16 v[16:31], v[64:67], v[190:193], v[16:31]
	v_exp_f32_e32 v241, v105
	ds_read_b64_tr_b16 v[190:191], v176 offset:34304
	ds_read_b64_tr_b16 v[192:193], v176 offset:36352
	s_waitcnt lgkmcnt(6)
	v_mfma_f32_32x32x16_bf16 v[16:31], v[68:71], v[194:197], v[16:31]
	v_exp_f32_e32 v242, v106
	ds_read_b64_tr_b16 v[194:195], v176 offset:38400
	ds_read_b64_tr_b16 v[196:197], v176 offset:40448
	s_waitcnt lgkmcnt(6)
	v_mfma_f32_32x32x16_bf16 v[16:31], v[72:75], v[200:203], v[16:31]
	v_exp_f32_e32 v243, v107
	ds_read_b64_tr_b16 v[200:201], v176 offset:42496
	ds_read_b64_tr_b16 v[202:203], v176 offset:44544
	ds_read_b64_tr_b16 v[208:209], v176 offset:46592
	ds_read_b64_tr_b16 v[210:211], v176 offset:48640
	s_waitcnt lgkmcnt(8)
	v_mfma_f32_32x32x16_bf16 v[16:31], v[76:79], v[204:207], v[16:31]
	v_exp_f32_e32 v244, v108
	s_waitcnt lgkmcnt(6)
	v_mfma_f32_32x32x16_bf16 v[0:15], v[64:67], v[190:193], v[0:15]
	v_exp_f32_e32 v245, v109
	s_waitcnt lgkmcnt(4)
	v_mfma_f32_32x32x16_bf16 v[0:15], v[68:71], v[194:197], v[0:15]
	v_exp_f32_e32 v246, v110
	s_waitcnt lgkmcnt(2)
	v_mfma_f32_32x32x16_bf16 v[0:15], v[72:75], v[200:203], v[0:15]
	v_exp_f32_e32 v247, v111
	s_waitcnt vmcnt(4)
	s_waitcnt lgkmcnt(0)
	s_barrier
	s_and_b32 s40, s40, 0xc000
	s_add_i32 s40, s57, s40
	ds_read_b128 v[64:67], v178
	ds_read_b128 v[68:71], v178 offset:8192
	ds_read_b128 v[190:193], v179
	ds_read_b128 v[194:197], v179 offset:8192
	v_mfma_f32_32x32x16_bf16 v[0:15], v[76:79], v[208:211], v[0:15]
	v_exp_f32_e32 v80, v80
	v_exp_f32_e32 v81, v81
	v_exp_f32_e32 v82, v82
	v_exp_f32_e32 v83, v83
	v_exp_f32_e32 v87, v87
	v_exp_f32_e32 v248, v93
	v_exp_f32_e32 v249, v94
	s_waitcnt lgkmcnt(3)
	v_mfma_f32_32x32x16_bf16 v[96:111], v[64:67], v[136:139], 0
	s_waitcnt lgkmcnt(2)
	v_mfma_f32_32x32x16_bf16 v[64:79], v[68:71], v[136:139], 0
	s_waitcnt lgkmcnt(1)
	v_mfma_f32_32x32x16_bf16 v[96:111], v[190:193], v[140:143], v[96:111]
	s_waitcnt lgkmcnt(0)
	v_mfma_f32_32x32x16_bf16 v[64:79], v[194:197], v[140:143], v[64:79]
	ds_read_b128 v[190:193], v180
	ds_read_b128 v[194:197], v180 offset:8192
	s_waitcnt lgkmcnt(1)
	v_mfma_f32_32x32x16_bf16 v[96:111], v[190:193], v[132:135], v[96:111]
	ds_read_b128 v[190:193], v181
	ds_read_b128 v[200:203], v181 offset:8192
	ds_read_b128 v[204:207], v182
	ds_read_b128 v[208:211], v182 offset:8192
	ds_read_b128 v[212:215], v183
	ds_read_b128 v[216:219], v183 offset:8192
	s_waitcnt lgkmcnt(6)
	v_mfma_f32_32x32x16_bf16 v[64:79], v[194:197], v[132:135], v[64:79]
	ds_read_b128 v[194:197], v184
	ds_read_b128 v[220:223], v184 offset:8192
	ds_read_b128 v[224:227], v185
	ds_read_b128 v[228:231], v185 offset:8192
	s_waitcnt lgkmcnt(9)
	v_mfma_f32_32x32x16_bf16 v[96:111], v[190:193], v[128:131], v[96:111]
	s_cmp_ge_u32 s73, s37
	s_cselect_b64 s[40:41], -1, 0
	s_and_b64 vcc, exec, s[40:41]
	s_cbranch_vccnz .Lat463_b

	s_add_i32 s74, s67, s43
	s_add_u32 s98, s38, s26
	s_addc_u32 s99, s39, s27
	s_mov_b32 m0, s74
	s_add_i32 s43, s72, s43
	global_load_lds_dwordx4 v156, s[98:99]
	s_add_u32 s100, s38, s28
	s_addc_u32 s101, s39, s29
	s_add_i32 m0, s74, 0x2000
	s_nop 0
	global_load_lds_dwordx4 v158, s[98:99]
	s_mov_b32 m0, s43
	s_nop 0
	global_load_lds_dwordx4 v162, s[100:101]
	s_add_i32 m0, s43, 0x2000
	s_nop 0
	global_load_lds_dwordx4 v160, s[100:101]

; __device__ __forceinline__ void finishSM(f32x16& p0, f32x16& p1, float alpha, float& l_reg, bf16x8& pa0, bf16x8& pa1, bf16x8& pa2, bf16x8& pa3) {
;   for (int r = 0; r < 16; ++r) p1[r] = __builtin_amdgcn_exp2f(p1[r]);
;   float ps = 0; for (int r = 0; r < 16; ++r) ps += p0[r]; for (int r = 0; r < 16; ++r) ps += p1[r];
;   asm volatile("" : "+v"(ps));
;   l_reg = l_reg * alpha + ps;
;     ...
;   PK4(p0, 0, pa0); PK4(p0, 8, pa1); PK4(p1, 0, pa2); PK4(p1, 8, pa3);
;     ...
; }
; __device__ __forceinline__ void qkt(f32x16& p0, f32x16& p1, const bf16* Ks, const bf16x8* qr, int r32, int hi) {
;   p0 = f32x16{}; p1 = f32x16{};
;   for (int d0 = 0; d0 < 8; ++d0) { int cb = (d0 * 16 + hi * 8) * 2;
;     bf16x8 b0 = *reinterpret_cast<const bf16x8*>((const char*)Ks + KSWZ(r32, cb));
;     bf16x8 b1 = *reinterpret_cast<const bf16x8*>((const char*)Ks + KSWZ(32 + r32, cb));
;     p0 = __builtin_amdgcn_mfma_f32_32x32x16_bf16(b0, qr[d0], p0, 0, 0, 0);
;     p1 = __builtin_amdgcn_mfma_f32_32x32x16_bf16(b1, qr[d0], p1, 0, 0, 0); }
; }
; __device__ __forceinline__ int v_st(int k, int c) { const int kk = k;
;   return ((kk >> 3) * 4 + (c >> 5)) * 512 + ((kk & 7) * 32 + (c & 31)) * 2; }
; __device__ __forceinline__ int v_rd_base(int lane) { return ((lane & 3) << 3) | (((lane >> 2) & 3) << 6) | (((lane >> 4) & 1) << 5) | (((lane >> 5) & 1) << 8); }
; template <int OFF> __device__ __forceinline__ s16x4 tr_read(int vb) {
;   s16x4 r; asm volatile("ds_read_b64_tr_b16 %0, %1 offset:%2" : "=&v"(r) : "v"(vb), "i"(OFF) : "memory"); return r;
; }
; template <int D0> __device__ __forceinline__ void pv_one(f32x16& od, int vb, bf16x8 pa0, bf16x8 pa1, bf16x8 pa2, bf16x8 pa3) {
;   const s16x4 l0 = tr_read<v_rd_off(D0, 0, 0)>(vb), h0 = tr_read<v_rd_off(D0, 0, 1)>(vb), l1 = tr_read<v_rd_off(D0, 1, 0)>(vb), h1 = tr_read<v_rd_off(D0, 1, 1)>(vb);
;   const s16x4 l2 = tr_read<v_rd_off(D0, 2, 0)>(vb), h2 = tr_read<v_rd_off(D0, 2, 1)>(vb), l3 = tr_read<v_rd_off(D0, 3, 0)>(vb), h3 = tr_read<v_rd_off(D0, 3, 1)>(vb);
;   asm volatile("s_waitcnt lgkmcnt(0)" ::: "memory"); SBAR();
;     ...
;   od = __builtin_amdgcn_mfma_f32_32x32x16_bf16(pa0, PK(l0, h0), od, 0, 0, 0);
;   od = __builtin_amdgcn_mfma_f32_32x32x16_bf16(pa1, PK(l1, h1), od, 0, 0, 0);
;   od = __builtin_amdgcn_mfma_f32_32x32x16_bf16(pa2, PK(l2, h2), od, 0, 0, 0);
;   od = __builtin_amdgcn_mfma_f32_32x32x16_bf16(pa3, PK(l3, h3), od, 0, 0, 0);
;     ...
; }
.Lat1365_a_go:
	s_waitcnt lgkmcnt(3)
	v_mfma_f32_32x32x16_bf16 v[96:111], v[80:83], v[136:139], 0
	v_exp_f32_e32 v238, v64
	v_add_f32_e32 v64, v197, v196
	v_add_f32_e32 v64, v193, v64
	v_add_f32_e32 v64, v195, v64
	s_waitcnt lgkmcnt(2)
	v_mfma_f32_32x32x16_bf16 v[80:95], v[84:87], v[136:139], 0
	v_add_f32_e32 v64, v191, v64
	v_add_f32_e32 v64, v194, v64
	v_add_f32_e32 v64, v190, v64
	v_add_f32_e32 v64, v192, v64
	v_add_f32_e32 v64, v169, v64
	v_add_f32_e32 v64, v171, v64
	s_waitcnt lgkmcnt(1)
	v_mfma_f32_32x32x16_bf16 v[96:111], v[198:201], v[140:143], v[96:111]
	v_add_f32_e32 v64, v167, v64
	v_add_f32_e32 v64, v170, v64
	v_add_f32_e32 v64, v165, v64
	v_add_f32_e32 v64, v168, v64
	v_add_f32_e32 v64, v164, v64
	v_add_f32_e32 v64, v166, v64
	v_exp_f32_e32 v239, v68
	s_waitcnt lgkmcnt(0)
	v_mfma_f32_32x32x16_bf16 v[80:95], v[202:205], v[140:143], v[80:95]
	ds_read_b128 v[198:201], v180 offset:16384
	ds_read_b128 v[202:205], v180 offset:24576
	v_add_f32_e32 v64, v238, v64
	v_exp_f32_e32 v240, v69
	v_exp_f32_e32 v241, v70
	v_exp_f32_e32 v242, v71
	s_waitcnt lgkmcnt(1)
	v_mfma_f32_32x32x16_bf16 v[96:111], v[198:201], v[132:135], v[96:111]
	ds_read_b128 v[198:201], v181 offset:16384
	ds_read_b128 v[206:209], v181 offset:24576
	ds_read_b128 v[210:213], v182 offset:16384
	ds_read_b128 v[214:217], v182 offset:24576
	ds_read_b128 v[218:221], v183 offset:16384
	ds_read_b128 v[222:225], v183 offset:24576
	v_exp_f32_e32 v243, v76
	v_exp_f32_e32 v244, v77
	v_exp_f32_e32 v245, v78
	v_exp_f32_e32 v79, v79
	s_waitcnt lgkmcnt(6)
	v_mfma_f32_32x32x16_bf16 v[80:95], v[202:205], v[132:135], v[80:95]
	ds_read_b128 v[202:205], v184 offset:16384
	ds_read_b128 v[226:229], v184 offset:24576
	ds_read_b128 v[230:233], v185 offset:16384
	ds_read_b128 v[234:237], v185 offset:24576
	s_waitcnt lgkmcnt(9)
	v_mfma_f32_32x32x16_bf16 v[96:111], v[198:201], v[128:131], v[96:111]
	v_exp_f32_e32 v199, v65
	v_exp_f32_e32 v200, v66
	v_exp_f32_e32 v201, v67
	v_add_f32_e32 v64, v199, v64
	v_add_f32_e32 v64, v200, v64
	v_add_f32_e32 v64, v201, v64
	s_waitcnt lgkmcnt(8)
	v_mfma_f32_32x32x16_bf16 v[80:95], v[206:209], v[128:131], v[80:95]
	v_exp_f32_e32 v206, v72
	v_add_f32_e32 v64, v239, v64
	v_exp_f32_e32 v207, v73
	v_add_f32_e32 v64, v240, v64
	v_exp_f32_e32 v208, v74
	v_add_f32_e32 v64, v241, v64
	v_exp_f32_e32 v209, v75
	s_waitcnt lgkmcnt(7)
	v_mfma_f32_32x32x16_bf16 v[96:111], v[210:213], v[124:127], v[96:111]
	v_add_f32_e32 v64, v242, v64
	v_add_f32_e32 v64, v206, v64
	v_add_f32_e32 v64, v207, v64
	v_add_f32_e32 v64, v208, v64
	v_add_f32_e32 v64, v209, v64
	v_add_f32_e32 v64, v243, v64
	v_add_f32_e32 v64, v244, v64
	s_waitcnt lgkmcnt(6)
	v_mfma_f32_32x32x16_bf16 v[80:95], v[214:217], v[124:127], v[80:95]
	v_add_f32_e32 v64, v245, v64
	v_add_f32_e32 v198, v79, v64
	v_cvt_pk_bf16_f32 v64, v196, v197
	v_cvt_pk_bf16_f32 v65, v193, v195
	v_cvt_pk_bf16_f32 v66, v191, v194
	v_cvt_pk_bf16_f32 v67, v190, v192
	s_waitcnt lgkmcnt(5)
	v_mfma_f32_32x32x16_bf16 v[96:111], v[218:221], v[120:123], v[96:111]
	v_cvt_pk_bf16_f32 v68, v169, v171
	v_cvt_pk_bf16_f32 v69, v167, v170
	v_cvt_pk_bf16_f32 v70, v165, v168
	v_cvt_pk_bf16_f32 v71, v164, v166
	v_cvt_pk_bf16_f32 v72, v238, v199
	v_cvt_pk_bf16_f32 v73, v200, v201
	v_cvt_pk_bf16_f32 v74, v239, v240
	s_waitcnt lgkmcnt(4)
	v_mfma_f32_32x32x16_bf16 v[80:95], v[222:225], v[120:123], v[80:95]
	v_cvt_pk_bf16_f32 v75, v241, v242
	v_cvt_pk_bf16_f32 v76, v206, v207
	v_cvt_pk_bf16_f32 v77, v208, v209
	v_cvt_pk_bf16_f32 v78, v243, v244
	v_cvt_pk_bf16_f32 v79, v245, v79
	s_waitcnt lgkmcnt(3)
	v_mfma_f32_32x32x16_bf16 v[96:111], v[202:205], v[116:119], v[96:111]
	s_add_i32 s33, s40, 0x8000
	s_and_b32 s43, s33, 0xc000
	ds_read_b64_tr_b16 v[190:191], v176
	ds_read_b64_tr_b16 v[192:193], v176 offset:2048
	ds_read_b64_tr_b16 v[194:195], v176 offset:4096
	ds_read_b64_tr_b16 v[196:197], v176 offset:6144
	s_waitcnt lgkmcnt(6)
	v_mfma_f32_32x32x16_bf16 v[80:95], v[226:229], v[116:119], v[80:95]
	ds_read_b64_tr_b16 v[200:201], v176 offset:8192
	ds_read_b64_tr_b16 v[202:203], v176 offset:10240
	ds_read_b64_tr_b16 v[204:205], v176 offset:12288
	ds_read_b64_tr_b16 v[206:207], v176 offset:14336
	s_add_i32 s73, s40, 0x4000
	s_and_b32 s73, s73, 0xc000
	s_add_u32 s98, s38, s22
	s_addc_u32 s99, s39, s23
	s_add_i32 s41, s66, s73
	s_add_u32 s100, s38, s24
	s_addc_u32 s101, s39, s25
	s_mov_b32 m0, s41
	s_add_i32 s73, s67, s73
	global_load_lds_dwordx4 v156, s[98:99]
	s_waitcnt lgkmcnt(9)
	v_mfma_f32_32x32x16_bf16 v[96:111], v[230:233], v[112:115], v[96:111]
	s_add_i32 m0, s41, 0x2000
	s_nop 0
	global_load_lds_dwordx4 v158, s[98:99]
	s_mov_b32 m0, s73
	s_nop 0
	global_load_lds_dwordx4 v162, s[100:101]
	s_waitcnt lgkmcnt(8)
	v_mfma_f32_32x32x16_bf16 v[80:95], v[234:237], v[112:115], v[80:95]
	s_add_i32 m0, s73, 0x2000
	s_nop 0
	global_load_lds_dwordx4 v160, s[100:101]
	s_nop 0
	s_waitcnt lgkmcnt(6)
	v_mfma_f32_32x32x16_bf16 v[48:63], v[64:67], v[190:193], v[48:63]
	v_exp_f32_e32 v232, v96
	ds_read_b64_tr_b16 v[190:191], v176 offset:512
	ds_read_b64_tr_b16 v[192:193], v176 offset:2560
	s_waitcnt lgkmcnt(6)
; #define SBAR() __builtin_amdgcn_sched_barrier(0)
; #define PUBLISH(n) do { asm volatile("s_waitcnt vmcnt(" #n ")" ::: "memory"); asm volatile("s_waitcnt lgkmcnt(0)" ::: "memory"); __builtin_amdgcn_s_barrier(); SBAR(); } while (0)
; template <int D0> __device__ __forceinline__ void pv_one(f32x16& od, int vb, bf16x8 pa0, bf16x8 pa1, bf16x8 pa2, bf16x8 pa3) {
;   const s16x4 l0 = tr_read<v_rd_off(D0, 0, 0)>(vb), h0 = tr_read<v_rd_off(D0, 0, 1)>(vb), l1 = tr_read<v_rd_off(D0, 1, 0)>(vb), h1 = tr_read<v_rd_off(D0, 1, 1)>(vb);
;   const s16x4 l2 = tr_read<v_rd_off(D0, 2, 0)>(vb), h2 = tr_read<v_rd_off(D0, 2, 1)>(vb), l3 = tr_read<v_rd_off(D0, 3, 0)>(vb), h3 = tr_read<v_rd_off(D0, 3, 1)>(vb);
;   asm volatile("s_waitcnt lgkmcnt(0)" ::: "memory"); SBAR();
;     ...
;   od = __builtin_amdgcn_mfma_f32_32x32x16_bf16(pa0, PK(l0, h0), od, 0, 0, 0);
;   od = __builtin_amdgcn_mfma_f32_32x32x16_bf16(pa1, PK(l1, h1), od, 0, 0, 0);
;   od = __builtin_amdgcn_mfma_f32_32x32x16_bf16(pa2, PK(l2, h2), od, 0, 0, 0);
;   od = __builtin_amdgcn_mfma_f32_32x32x16_bf16(pa3, PK(l3, h3), od, 0, 0, 0);
;     ...
; }
; __device__ __forceinline__ void pv_d0(f32x16* o, int vb, bf16x8 pa0, bf16x8 pa1, bf16x8 pa2, bf16x8 pa3) {
;   pv_one<0>(o[0], vb, pa0, pa1, pa2, pa3); pv_one<1>(o[1], vb, pa0, pa1, pa2, pa3); pv_one<2>(o[2], vb, pa0, pa1, pa2, pa3); pv_one<3>(o[3], vb, pa0, pa1, pa2, pa3);
; }
; template <typename TQ> ...
;     ...
;   for (int j = 1; j + 1 < NT; j += 2) {
;     SBAR(); qkt(pB0, pB1, (const bf16*)(K_lds + (j & 3) * (int)SHM_K), qr, r32, hi);
;     finishSM(pA0, pA1, alA, l_reg, pa0, pa1, pa2, pa3); SBAR();
;     DMA_TILE(j + 2, (j + 2) & 3); SBAR();
;     pv_d0(o, vb0 + ((j - 1) & 3) * (int)SHM_V, pa0, pa1, pa2, pa3); partialSM<true>(pB0, pB1, m_reg, mnB, alB);
;     PUBLISH(4);
;     SBAR(); qkt(pA0, pA1, (const bf16*)(K_lds + ((j + 1) & 3) * (int)SHM_K), qr, r32, hi);
;     finishSM(pB0, pB1, alB, l_reg, pa0, pa1, pa2, pa3); SBAR();
;     if (j + 3 < NT) { DMA_TILE(j + 3, (j + 3) & 3); } SBAR();
	v_mfma_f32_32x32x16_bf16 v[48:63], v[68:71], v[194:197], v[48:63]
	v_exp_f32_e32 v233, v97
	ds_read_b64_tr_b16 v[194:195], v176 offset:4608
	ds_read_b64_tr_b16 v[196:197], v176 offset:6656
	s_waitcnt lgkmcnt(6)
	v_mfma_f32_32x32x16_bf16 v[48:63], v[72:75], v[200:203], v[48:63]
	v_exp_f32_e32 v234, v98
	ds_read_b64_tr_b16 v[200:201], v176 offset:8704
	ds_read_b64_tr_b16 v[202:203], v176 offset:10752
	ds_read_b64_tr_b16 v[208:209], v176 offset:12800
	ds_read_b64_tr_b16 v[210:211], v176 offset:14848
	s_waitcnt lgkmcnt(8)
	v_mfma_f32_32x32x16_bf16 v[48:63], v[76:79], v[204:207], v[48:63]
	v_exp_f32_e32 v235, v99
	s_waitcnt lgkmcnt(6)
	v_mfma_f32_32x32x16_bf16 v[32:47], v[64:67], v[190:193], v[32:47]
	v_exp_f32_e32 v236, v100
	ds_read_b64_tr_b16 v[190:191], v176 offset:1024
	ds_read_b64_tr_b16 v[192:193], v176 offset:3072
	s_waitcnt lgkmcnt(6)
	v_mfma_f32_32x32x16_bf16 v[32:47], v[68:71], v[194:197], v[32:47]
	v_exp_f32_e32 v237, v101
	ds_read_b64_tr_b16 v[194:195], v176 offset:5120
	ds_read_b64_tr_b16 v[196:197], v176 offset:7168
	s_waitcnt lgkmcnt(6)
	v_mfma_f32_32x32x16_bf16 v[32:47], v[72:75], v[200:203], v[32:47]
	v_exp_f32_e32 v238, v102
	ds_read_b64_tr_b16 v[200:201], v176 offset:9216
	ds_read_b64_tr_b16 v[202:203], v176 offset:11264
	ds_read_b64_tr_b16 v[204:205], v176 offset:13312
	ds_read_b64_tr_b16 v[206:207], v176 offset:15360
	s_waitcnt lgkmcnt(8)
	v_mfma_f32_32x32x16_bf16 v[32:47], v[76:79], v[208:211], v[32:47]
	v_exp_f32_e32 v239, v103
	v_exp_f32_e32 v240, v104
	s_waitcnt lgkmcnt(6)
	v_mfma_f32_32x32x16_bf16 v[16:31], v[64:67], v[190:193], v[16:31]
	v_exp_f32_e32 v241, v105
	ds_read_b64_tr_b16 v[190:191], v176 offset:1536
	ds_read_b64_tr_b16 v[192:193], v176 offset:3584
	s_waitcnt lgkmcnt(6)
	v_mfma_f32_32x32x16_bf16 v[16:31], v[68:71], v[194:197], v[16:31]
	v_exp_f32_e32 v242, v106
	ds_read_b64_tr_b16 v[194:195], v176 offset:5632
	ds_read_b64_tr_b16 v[196:197], v176 offset:7680
	s_waitcnt lgkmcnt(6)
	v_mfma_f32_32x32x16_bf16 v[16:31], v[72:75], v[200:203], v[16:31]
	v_exp_f32_e32 v243, v107
	ds_read_b64_tr_b16 v[200:201], v176 offset:9728
	ds_read_b64_tr_b16 v[202:203], v176 offset:11776
	ds_read_b64_tr_b16 v[208:209], v176 offset:13824
	ds_read_b64_tr_b16 v[210:211], v176 offset:15872
	s_waitcnt lgkmcnt(8)
	v_mfma_f32_32x32x16_bf16 v[16:31], v[76:79], v[204:207], v[16:31]
	v_exp_f32_e32 v244, v108
	s_waitcnt lgkmcnt(6)
	v_mfma_f32_32x32x16_bf16 v[0:15], v[64:67], v[190:193], v[0:15]
	v_exp_f32_e32 v245, v109
	s_waitcnt lgkmcnt(4)
	v_mfma_f32_32x32x16_bf16 v[0:15], v[68:71], v[194:197], v[0:15]
	v_exp_f32_e32 v246, v110
	s_waitcnt lgkmcnt(2)
	v_mfma_f32_32x32x16_bf16 v[0:15], v[72:75], v[200:203], v[0:15]
	v_exp_f32_e32 v247, v111
	s_waitcnt vmcnt(4)
	s_waitcnt lgkmcnt(0)
	s_barrier
	s_and_b32 s40, s40, 0xc000
	s_add_i32 s40, s56, s40
	ds_read_b128 v[64:67], v178 offset:32768
	ds_read_b128 v[68:71], v178 offset:40960
	ds_read_b128 v[190:193], v179 offset:32768
	ds_read_b128 v[194:197], v179 offset:40960
	v_mfma_f32_32x32x16_bf16 v[0:15], v[76:79], v[208:211], v[0:15]
	v_exp_f32_e32 v80, v80
	v_exp_f32_e32 v81, v81
	v_exp_f32_e32 v82, v82
	v_exp_f32_e32 v83, v83
	v_exp_f32_e32 v87, v87
	v_exp_f32_e32 v248, v93
	v_exp_f32_e32 v249, v94
	s_waitcnt lgkmcnt(3)
	v_mfma_f32_32x32x16_bf16 v[96:111], v[64:67], v[136:139], 0
	s_waitcnt lgkmcnt(2)
	v_mfma_f32_32x32x16_bf16 v[64:79], v[68:71], v[136:139], 0
	s_waitcnt lgkmcnt(1)
	v_mfma_f32_32x32x16_bf16 v[96:111], v[190:193], v[140:143], v[96:111]
	s_waitcnt lgkmcnt(0)
	v_mfma_f32_32x32x16_bf16 v[64:79], v[194:197], v[140:143], v[64:79]
	ds_read_b128 v[190:193], v180 offset:32768
	ds_read_b128 v[194:197], v180 offset:40960
	s_waitcnt lgkmcnt(1)
	v_mfma_f32_32x32x16_bf16 v[96:111], v[190:193], v[132:135], v[96:111]
	ds_read_b128 v[190:193], v181 offset:32768
	ds_read_b128 v[200:203], v181 offset:40960
	ds_read_b128 v[204:207], v182 offset:32768
	ds_read_b128 v[208:211], v182 offset:40960
	ds_read_b128 v[212:215], v183 offset:32768
	ds_read_b128 v[216:219], v183 offset:40960
	s_waitcnt lgkmcnt(6)
	v_mfma_f32_32x32x16_bf16 v[64:79], v[194:197], v[132:135], v[64:79]
	ds_read_b128 v[194:197], v184 offset:32768
	ds_read_b128 v[220:223], v184 offset:40960
	ds_read_b128 v[224:227], v185 offset:32768
	ds_read_b128 v[228:231], v185 offset:40960
	s_waitcnt lgkmcnt(9)
	v_mfma_f32_32x32x16_bf16 v[96:111], v[190:193], v[128:131], v[96:111]
	s_cmp_ge_u32 s72, s37
	s_cselect_b64 s[40:41], -1, 0
	s_and_b64 vcc, exec, s[40:41]
	s_cbranch_vccnz .LBB0_1367
	s_add_i32 s73, s66, s43
	s_add_u32 s98, s38, s26
	s_addc_u32 s99, s39, s27
	s_mov_b32 m0, s73
	s_add_i32 s43, s67, s43
	global_load_lds_dwordx4 v156, s[98:99]
	s_add_u32 s100, s38, s28
	s_addc_u32 s101, s39, s29
	s_add_i32 m0, s73, 0x2000
	s_nop 0
	global_load_lds_dwordx4 v158, s[98:99]
	s_mov_b32 m0, s43
	s_nop 0
	global_load_lds_dwordx4 v162, s[100:101]
	s_add_i32 m0, s43, 0x2000
	s_nop 0
	global_load_lds_dwordx4 v160, s[100:101]

; #define SBAR() __builtin_amdgcn_sched_barrier(0)
; #define PK4(P, BASE, OUT) do { u32x4 w = {cvtpk(P[BASE + 0], P[BASE + 1]), cvtpk(P[BASE + 2], P[BASE + 3]), cvtpk(P[BASE + 4], P[BASE + 5]), cvtpk(P[BASE + 6], P[BASE + 7])}; \
;     OUT = *reinterpret_cast<bf16x8*>(&w); } while (0)
; __device__ __forceinline__ void finishSM(f32x16& p0, f32x16& p1, float alpha, float& l_reg, bf16x8& pa0, bf16x8& pa1, bf16x8& pa2, bf16x8& pa3) {
;   for (int r = 0; r < 16; ++r) p1[r] = __builtin_amdgcn_exp2f(p1[r]);
;   float ps = 0; for (int r = 0; r < 16; ++r) ps += p0[r]; for (int r = 0; r < 16; ++r) ps += p1[r];
;   asm volatile("" : "+v"(ps));
;   l_reg = l_reg * alpha + ps;
;     ...
;   PK4(p0, 0, pa0); PK4(p0, 8, pa1); PK4(p1, 0, pa2); PK4(p1, 8, pa3);
;     ...
; }
; __device__ __forceinline__ void qkt(f32x16& p0, f32x16& p1, const bf16* Ks, const bf16x8* qr, int r32, int hi) {
;   p0 = f32x16{}; p1 = f32x16{};
;   for (int d0 = 0; d0 < 8; ++d0) { int cb = (d0 * 16 + hi * 8) * 2;
;     bf16x8 b0 = *reinterpret_cast<const bf16x8*>((const char*)Ks + KSWZ(r32, cb));
;     bf16x8 b1 = *reinterpret_cast<const bf16x8*>((const char*)Ks + KSWZ(32 + r32, cb));
;     p0 = __builtin_amdgcn_mfma_f32_32x32x16_bf16(b0, qr[d0], p0, 0, 0, 0);
;     p1 = __builtin_amdgcn_mfma_f32_32x32x16_bf16(b1, qr[d0], p1, 0, 0, 0); }
; }
; template <typename TQ> ...
;     ...
;   for (int j = 1; j + 1 < NT; j += 2) {
;     SBAR(); qkt(pB0, pB1, (const bf16*)(K_lds + (j & 3) * (int)SHM_K), qr, r32, hi);
;     finishSM(pA0, pA1, alA, l_reg, pa0, pa1, pa2, pa3); SBAR();
;     DMA_TILE(j + 2, (j + 2) & 3); SBAR();
;     pv_d0(o, vb0 + ((j - 1) & 3) * (int)SHM_V, pa0, pa1, pa2, pa3); partialSM<true>(pB0, pB1, m_reg, mnB, alB);
.Lat1365_b:
.Lat1365_b_in:
	s_mov_b32 s40, s33
	s_addk_i32 s33, 0xc000
	s_and_b32 s42, s33, 0xc000
	s_add_i32 s33, s56, s42
	ds_read_b128 v[80:83], v178 offset:49152
	ds_read_b128 v[84:87], v178 offset:57344
	ds_read_b128 v[198:201], v179 offset:49152
	ds_read_b128 v[202:205], v179 offset:57344
	v_exp_f32_e32 v196, v96
	v_exp_f32_e32 v197, v97
	v_exp_f32_e32 v193, v98
	v_exp_f32_e32 v195, v99
	v_exp_f32_e32 v191, v100
	v_exp_f32_e32 v194, v101
	v_exp_f32_e32 v190, v102
	v_exp_f32_e32 v192, v103
	v_exp_f32_e32 v169, v104
	v_exp_f32_e32 v171, v105
	v_exp_f32_e32 v167, v106
	v_exp_f32_e32 v170, v107
	v_exp_f32_e32 v165, v108
	v_exp_f32_e32 v168, v109
	v_exp_f32_e32 v164, v110
	v_exp_f32_e32 v166, v111
	s_waitcnt lgkmcnt(3)
	v_mfma_f32_32x32x16_bf16 v[96:111], v[80:83], v[136:139], 0
	v_exp_f32_e32 v238, v64
	v_add_f32_e32 v64, v197, v196
	v_add_f32_e32 v64, v193, v64
	v_add_f32_e32 v64, v195, v64
	s_waitcnt lgkmcnt(2)
	v_mfma_f32_32x32x16_bf16 v[80:95], v[84:87], v[136:139], 0
	v_add_f32_e32 v64, v191, v64
	v_add_f32_e32 v64, v194, v64
	v_add_f32_e32 v64, v190, v64
	v_add_f32_e32 v64, v192, v64
	v_add_f32_e32 v64, v169, v64
	v_add_f32_e32 v64, v171, v64
	s_waitcnt lgkmcnt(1)
	v_mfma_f32_32x32x16_bf16 v[96:111], v[198:201], v[140:143], v[96:111]
	v_add_f32_e32 v64, v167, v64
	v_add_f32_e32 v64, v170, v64
	v_add_f32_e32 v64, v165, v64
	v_add_f32_e32 v64, v168, v64
	v_add_f32_e32 v64, v164, v64
	v_add_f32_e32 v64, v166, v64
	v_exp_f32_e32 v239, v68
	s_waitcnt lgkmcnt(0)
	v_mfma_f32_32x32x16_bf16 v[80:95], v[202:205], v[140:143], v[80:95]
	ds_read_b128 v[198:201], v180 offset:49152
	ds_read_b128 v[202:205], v180 offset:57344
	v_add_f32_e32 v64, v238, v64
	v_exp_f32_e32 v240, v69
	v_exp_f32_e32 v241, v70
	v_exp_f32_e32 v242, v71
	s_waitcnt lgkmcnt(1)
	v_mfma_f32_32x32x16_bf16 v[96:111], v[198:201], v[132:135], v[96:111]
	ds_read_b128 v[198:201], v181 offset:49152
	ds_read_b128 v[206:209], v181 offset:57344
	ds_read_b128 v[210:213], v182 offset:49152
	ds_read_b128 v[214:217], v182 offset:57344
	ds_read_b128 v[218:221], v183 offset:49152
	ds_read_b128 v[222:225], v183 offset:57344
	v_exp_f32_e32 v243, v76
	v_exp_f32_e32 v244, v77
	v_exp_f32_e32 v245, v78
	v_exp_f32_e32 v79, v79
	s_waitcnt lgkmcnt(6)
	v_mfma_f32_32x32x16_bf16 v[80:95], v[202:205], v[132:135], v[80:95]
	ds_read_b128 v[202:205], v184 offset:49152
	ds_read_b128 v[226:229], v184 offset:57344
	ds_read_b128 v[230:233], v185 offset:49152
	ds_read_b128 v[234:237], v185 offset:57344
	s_waitcnt lgkmcnt(9)
	v_mfma_f32_32x32x16_bf16 v[96:111], v[198:201], v[128:131], v[96:111]
	v_exp_f32_e32 v199, v65
	v_exp_f32_e32 v200, v66
	v_exp_f32_e32 v201, v67
	v_add_f32_e32 v64, v199, v64
	v_add_f32_e32 v64, v200, v64
	v_add_f32_e32 v64, v201, v64
	s_waitcnt lgkmcnt(8)
	v_mfma_f32_32x32x16_bf16 v[80:95], v[206:209], v[128:131], v[80:95]
	v_exp_f32_e32 v206, v72
	v_add_f32_e32 v64, v239, v64
	v_exp_f32_e32 v207, v73
	v_add_f32_e32 v64, v240, v64
	v_exp_f32_e32 v208, v74
	v_add_f32_e32 v64, v241, v64
	v_exp_f32_e32 v209, v75
	s_waitcnt lgkmcnt(7)
	v_mfma_f32_32x32x16_bf16 v[96:111], v[210:213], v[124:127], v[96:111]
	v_add_f32_e32 v64, v242, v64
	v_add_f32_e32 v64, v206, v64
	v_add_f32_e32 v64, v207, v64
	v_add_f32_e32 v64, v208, v64
	v_add_f32_e32 v64, v209, v64
	v_add_f32_e32 v64, v243, v64
	v_add_f32_e32 v64, v244, v64
	s_waitcnt lgkmcnt(6)
	v_mfma_f32_32x32x16_bf16 v[80:95], v[214:217], v[124:127], v[80:95]
	v_add_f32_e32 v64, v245, v64
	v_add_f32_e32 v198, v79, v64
	v_cvt_pk_bf16_f32 v64, v196, v197
	v_cvt_pk_bf16_f32 v65, v193, v195
	v_cvt_pk_bf16_f32 v66, v191, v194
	v_cvt_pk_bf16_f32 v67, v190, v192
	s_waitcnt lgkmcnt(5)
	v_mfma_f32_32x32x16_bf16 v[96:111], v[218:221], v[120:123], v[96:111]
	v_cvt_pk_bf16_f32 v68, v169, v171
	v_cvt_pk_bf16_f32 v69, v167, v170
	v_cvt_pk_bf16_f32 v70, v165, v168
	v_cvt_pk_bf16_f32 v71, v164, v166
	v_cvt_pk_bf16_f32 v72, v238, v199
	v_cvt_pk_bf16_f32 v73, v200, v201
	v_cvt_pk_bf16_f32 v74, v239, v240
	s_waitcnt lgkmcnt(4)
	v_mfma_f32_32x32x16_bf16 v[80:95], v[222:225], v[120:123], v[80:95]
	v_cvt_pk_bf16_f32 v75, v241, v242
	v_cvt_pk_bf16_f32 v76, v206, v207
	v_cvt_pk_bf16_f32 v77, v208, v209
	v_cvt_pk_bf16_f32 v78, v243, v244
	v_cvt_pk_bf16_f32 v79, v245, v79
	s_waitcnt lgkmcnt(3)
	v_mfma_f32_32x32x16_bf16 v[96:111], v[202:205], v[116:119], v[96:111]
	s_add_i32 s33, s40, 0x8000
	s_and_b32 s43, s33, 0xc000
	ds_read_b64_tr_b16 v[190:191], v176 offset:32768
	ds_read_b64_tr_b16 v[192:193], v176 offset:34816
	ds_read_b64_tr_b16 v[194:195], v176 offset:36864
	ds_read_b64_tr_b16 v[196:197], v176 offset:38912
	s_waitcnt lgkmcnt(6)
	v_mfma_f32_32x32x16_bf16 v[80:95], v[226:229], v[116:119], v[80:95]
	ds_read_b64_tr_b16 v[200:201], v176 offset:40960
	ds_read_b64_tr_b16 v[202:203], v176 offset:43008
	ds_read_b64_tr_b16 v[204:205], v176 offset:45056
	ds_read_b64_tr_b16 v[206:207], v176 offset:47104
	s_add_i32 s73, s40, 0x4000
	s_and_b32 s73, s73, 0xc000
	s_add_u32 s98, s38, s22
	s_addc_u32 s99, s39, s23
	s_add_i32 s41, s66, s73
	s_add_u32 s100, s38, s24
	s_addc_u32 s101, s39, s25
	s_mov_b32 m0, s41
	s_add_i32 s73, s67, s73
	global_load_lds_dwordx4 v156, s[98:99]
	s_waitcnt lgkmcnt(9)
; #define SBAR() __builtin_amdgcn_sched_barrier(0)
; #define PUBLISH(n) do { asm volatile("s_waitcnt vmcnt(" #n ")" ::: "memory"); asm volatile("s_waitcnt lgkmcnt(0)" ::: "memory"); __builtin_amdgcn_s_barrier(); SBAR(); } while (0)
; template <int D0> __device__ __forceinline__ void pv_one(f32x16& od, int vb, bf16x8 pa0, bf16x8 pa1, bf16x8 pa2, bf16x8 pa3) {
;   const s16x4 l0 = tr_read<v_rd_off(D0, 0, 0)>(vb), h0 = tr_read<v_rd_off(D0, 0, 1)>(vb), l1 = tr_read<v_rd_off(D0, 1, 0)>(vb), h1 = tr_read<v_rd_off(D0, 1, 1)>(vb);
;   const s16x4 l2 = tr_read<v_rd_off(D0, 2, 0)>(vb), h2 = tr_read<v_rd_off(D0, 2, 1)>(vb), l3 = tr_read<v_rd_off(D0, 3, 0)>(vb), h3 = tr_read<v_rd_off(D0, 3, 1)>(vb);
;   asm volatile("s_waitcnt lgkmcnt(0)" ::: "memory"); SBAR();
;     ...
;   od = __builtin_amdgcn_mfma_f32_32x32x16_bf16(pa0, PK(l0, h0), od, 0, 0, 0);
;   od = __builtin_amdgcn_mfma_f32_32x32x16_bf16(pa1, PK(l1, h1), od, 0, 0, 0);
;   od = __builtin_amdgcn_mfma_f32_32x32x16_bf16(pa2, PK(l2, h2), od, 0, 0, 0);
;   od = __builtin_amdgcn_mfma_f32_32x32x16_bf16(pa3, PK(l3, h3), od, 0, 0, 0);
;     ...
; }
; __device__ __forceinline__ void pv_d0(f32x16* o, int vb, bf16x8 pa0, bf16x8 pa1, bf16x8 pa2, bf16x8 pa3) {
;   pv_one<0>(o[0], vb, pa0, pa1, pa2, pa3); pv_one<1>(o[1], vb, pa0, pa1, pa2, pa3); pv_one<2>(o[2], vb, pa0, pa1, pa2, pa3); pv_one<3>(o[3], vb, pa0, pa1, pa2, pa3);
; }
; template <typename TQ> ...
;     ...
;   for (int j = 1; j + 1 < NT; j += 2) {
;     SBAR(); qkt(pB0, pB1, (const bf16*)(K_lds + (j & 3) * (int)SHM_K), qr, r32, hi);
;     finishSM(pA0, pA1, alA, l_reg, pa0, pa1, pa2, pa3); SBAR();
;     DMA_TILE(j + 2, (j + 2) & 3); SBAR();
;     pv_d0(o, vb0 + ((j - 1) & 3) * (int)SHM_V, pa0, pa1, pa2, pa3); partialSM<true>(pB0, pB1, m_reg, mnB, alB);
;     PUBLISH(4);
;     SBAR(); qkt(pA0, pA1, (const bf16*)(K_lds + ((j + 1) & 3) * (int)SHM_K), qr, r32, hi);
;     finishSM(pB0, pB1, alB, l_reg, pa0, pa1, pa2, pa3); SBAR();
;     if (j + 3 < NT) { DMA_TILE(j + 3, (j + 3) & 3); } SBAR();
	v_mfma_f32_32x32x16_bf16 v[96:111], v[230:233], v[112:115], v[96:111]
	s_add_i32 m0, s41, 0x2000
	s_nop 0
	global_load_lds_dwordx4 v158, s[98:99]
	s_mov_b32 m0, s73
	s_nop 0
	global_load_lds_dwordx4 v162, s[100:101]
	s_waitcnt lgkmcnt(8)
	v_mfma_f32_32x32x16_bf16 v[80:95], v[234:237], v[112:115], v[80:95]
	s_add_i32 m0, s73, 0x2000
	s_nop 0
	global_load_lds_dwordx4 v160, s[100:101]
	s_nop 0
	s_waitcnt lgkmcnt(6)
	v_mfma_f32_32x32x16_bf16 v[48:63], v[64:67], v[190:193], v[48:63]
	v_exp_f32_e32 v232, v96
	ds_read_b64_tr_b16 v[190:191], v176 offset:33280
	ds_read_b64_tr_b16 v[192:193], v176 offset:35328
	s_waitcnt lgkmcnt(6)
	v_mfma_f32_32x32x16_bf16 v[48:63], v[68:71], v[194:197], v[48:63]
	v_exp_f32_e32 v233, v97
	ds_read_b64_tr_b16 v[194:195], v176 offset:37376
	ds_read_b64_tr_b16 v[196:197], v176 offset:39424
	s_waitcnt lgkmcnt(6)
	v_mfma_f32_32x32x16_bf16 v[48:63], v[72:75], v[200:203], v[48:63]
	v_exp_f32_e32 v234, v98
	ds_read_b64_tr_b16 v[200:201], v176 offset:41472
	ds_read_b64_tr_b16 v[202:203], v176 offset:43520
	ds_read_b64_tr_b16 v[208:209], v176 offset:45568
	ds_read_b64_tr_b16 v[210:211], v176 offset:47616
	s_waitcnt lgkmcnt(8)
	v_mfma_f32_32x32x16_bf16 v[48:63], v[76:79], v[204:207], v[48:63]
	v_exp_f32_e32 v235, v99
	s_waitcnt lgkmcnt(6)
	v_mfma_f32_32x32x16_bf16 v[32:47], v[64:67], v[190:193], v[32:47]
	v_exp_f32_e32 v236, v100
	ds_read_b64_tr_b16 v[190:191], v176 offset:33792
	ds_read_b64_tr_b16 v[192:193], v176 offset:35840
	s_waitcnt lgkmcnt(6)
	v_mfma_f32_32x32x16_bf16 v[32:47], v[68:71], v[194:197], v[32:47]
	v_exp_f32_e32 v237, v101
	ds_read_b64_tr_b16 v[194:195], v176 offset:37888
	ds_read_b64_tr_b16 v[196:197], v176 offset:39936
	s_waitcnt lgkmcnt(6)
	v_mfma_f32_32x32x16_bf16 v[32:47], v[72:75], v[200:203], v[32:47]
	v_exp_f32_e32 v238, v102
	ds_read_b64_tr_b16 v[200:201], v176 offset:41984
	ds_read_b64_tr_b16 v[202:203], v176 offset:44032
	ds_read_b64_tr_b16 v[204:205], v176 offset:46080
	ds_read_b64_tr_b16 v[206:207], v176 offset:48128
	s_waitcnt lgkmcnt(8)
	v_mfma_f32_32x32x16_bf16 v[32:47], v[76:79], v[208:211], v[32:47]
	v_exp_f32_e32 v239, v103
	v_exp_f32_e32 v240, v104
	s_waitcnt lgkmcnt(6)
	v_mfma_f32_32x32x16_bf16 v[16:31], v[64:67], v[190:193], v[16:31]
	v_exp_f32_e32 v241, v105
	ds_read_b64_tr_b16 v[190:191], v176 offset:34304
	ds_read_b64_tr_b16 v[192:193], v176 offset:36352
	s_waitcnt lgkmcnt(6)
	v_mfma_f32_32x32x16_bf16 v[16:31], v[68:71], v[194:197], v[16:31]
	v_exp_f32_e32 v242, v106
	ds_read_b64_tr_b16 v[194:195], v176 offset:38400
	ds_read_b64_tr_b16 v[196:197], v176 offset:40448
	s_waitcnt lgkmcnt(6)
	v_mfma_f32_32x32x16_bf16 v[16:31], v[72:75], v[200:203], v[16:31]
	v_exp_f32_e32 v243, v107
	ds_read_b64_tr_b16 v[200:201], v176 offset:42496
	ds_read_b64_tr_b16 v[202:203], v176 offset:44544
	ds_read_b64_tr_b16 v[208:209], v176 offset:46592
	ds_read_b64_tr_b16 v[210:211], v176 offset:48640
	s_waitcnt lgkmcnt(8)
	v_mfma_f32_32x32x16_bf16 v[16:31], v[76:79], v[204:207], v[16:31]
	v_exp_f32_e32 v244, v108
	s_waitcnt lgkmcnt(6)
	v_mfma_f32_32x32x16_bf16 v[0:15], v[64:67], v[190:193], v[0:15]
	v_exp_f32_e32 v245, v109
	s_waitcnt lgkmcnt(4)
	v_mfma_f32_32x32x16_bf16 v[0:15], v[68:71], v[194:197], v[0:15]
	v_exp_f32_e32 v246, v110
	s_waitcnt lgkmcnt(2)
	v_mfma_f32_32x32x16_bf16 v[0:15], v[72:75], v[200:203], v[0:15]
	v_exp_f32_e32 v247, v111
	s_waitcnt vmcnt(4)
	s_waitcnt lgkmcnt(0)
	s_barrier
	s_and_b32 s40, s40, 0xc000
	s_add_i32 s40, s56, s40
	ds_read_b128 v[64:67], v178
	ds_read_b128 v[68:71], v178 offset:8192
	ds_read_b128 v[190:193], v179
	ds_read_b128 v[194:197], v179 offset:8192
	v_mfma_f32_32x32x16_bf16 v[0:15], v[76:79], v[208:211], v[0:15]
	v_exp_f32_e32 v80, v80
	v_exp_f32_e32 v81, v81
	v_exp_f32_e32 v82, v82
	v_exp_f32_e32 v83, v83
	v_exp_f32_e32 v87, v87
	v_exp_f32_e32 v248, v93
	v_exp_f32_e32 v249, v94
	s_waitcnt lgkmcnt(3)
	v_mfma_f32_32x32x16_bf16 v[96:111], v[64:67], v[136:139], 0
	s_waitcnt lgkmcnt(2)
	v_mfma_f32_32x32x16_bf16 v[64:79], v[68:71], v[136:139], 0
	s_waitcnt lgkmcnt(1)
	v_mfma_f32_32x32x16_bf16 v[96:111], v[190:193], v[140:143], v[96:111]
	s_waitcnt lgkmcnt(0)
	v_mfma_f32_32x32x16_bf16 v[64:79], v[194:197], v[140:143], v[64:79]
	ds_read_b128 v[190:193], v180
	ds_read_b128 v[194:197], v180 offset:8192
	s_waitcnt lgkmcnt(1)
	v_mfma_f32_32x32x16_bf16 v[96:111], v[190:193], v[132:135], v[96:111]
	ds_read_b128 v[190:193], v181
	ds_read_b128 v[200:203], v181 offset:8192
	ds_read_b128 v[204:207], v182
	ds_read_b128 v[208:211], v182 offset:8192
	ds_read_b128 v[212:215], v183
	ds_read_b128 v[216:219], v183 offset:8192
	s_waitcnt lgkmcnt(6)
	v_mfma_f32_32x32x16_bf16 v[64:79], v[194:197], v[132:135], v[64:79]
	ds_read_b128 v[194:197], v184
	ds_read_b128 v[220:223], v184 offset:8192
	ds_read_b128 v[224:227], v185
	ds_read_b128 v[228:231], v185 offset:8192
	s_waitcnt lgkmcnt(9)
	v_mfma_f32_32x32x16_bf16 v[96:111], v[190:193], v[128:131], v[96:111]
	s_cmp_ge_u32 s72, s37
	s_cselect_b64 s[40:41], -1, 0
	s_and_b64 vcc, exec, s[40:41]
	s_cbranch_vccnz .Lat1367_b

	s_add_i32 s73, s66, s43
	s_add_u32 s98, s38, s26
	s_addc_u32 s99, s39, s27
	s_mov_b32 m0, s73
	s_add_i32 s43, s67, s43
	global_load_lds_dwordx4 v156, s[98:99]
	s_add_u32 s100, s38, s28
	s_addc_u32 s101, s39, s29
	s_add_i32 m0, s73, 0x2000
	s_nop 0
	global_load_lds_dwordx4 v158, s[98:99]
	s_mov_b32 m0, s43
	s_nop 0
	global_load_lds_dwordx4 v162, s[100:101]
	s_add_i32 m0, s43, 0x2000
	s_nop 0
	global_load_lds_dwordx4 v160, s[100:101]
